# VW1: attention V staging re-assigned so that 16 lanes write 256 contiguous LDS bytes (no bank conflicts on the V ds_write_b128; LDS image unchanged); on top of BE1
# baseline (speedup 1.0000x reference)
.LBB0_626:
	v_mov_b32_e32 v4, v0
	s_lshl_b64 s[8:9], s[18:19], 12
	s_add_u32 s8, s4, s8
	v_ashrrev_i32_e32 v167, 6, v4
	v_and_b32_e32 v165, 31, v4
	v_lshlrev_b32_e32 v164, 5, v167
	s_addc_u32 s9, s5, s9
	s_lshl_b32 s18, s30, 8
	v_or_b32_e32 v6, v164, v165
	s_add_u32 s40, s8, s18
	v_ashrrev_i32_e32 v7, 31, v6
	s_addc_u32 s41, s9, 0
	v_bfe_u32 v170, v4, 5, 1
	v_lshlrev_b64 v[6:7], 12, v[6:7]
	v_lshl_add_u64 v[6:7], s[40:41], 0, v[6:7]
	v_lshlrev_b32_e32 v168, 4, v170
	v_mov_b32_e32 v169, v3
	s_lshl_b64 s[8:9], s[16:17], 10
	v_lshl_add_u64 v[6:7], v[6:7], 0, v[168:169]
	v_ashrrev_i32_e32 v5, 4, v4
	s_add_u32 s18, s14, s8
	global_load_dwordx4 v[128:131], v[6:7], off
	global_load_dwordx4 v[124:127], v[6:7], off offset:32
	global_load_dwordx4 v[120:123], v[6:7], off offset:64
	global_load_dwordx4 v[116:119], v[6:7], off offset:96
	global_load_dwordx4 v[112:115], v[6:7], off offset:128
	global_load_dwordx4 v[108:111], v[6:7], off offset:160
	global_load_dwordx4 v[104:107], v[6:7], off offset:192
	global_load_dwordx4 v[100:103], v[6:7], off offset:224
	v_and_b32_e32 v7, 0xfffff8, v5
	v_lshlrev_b32_e32 v8, 1, v5
	s_addc_u32 s19, s15, s9
	s_lshl_b64 s[16:17], s[36:37], 1
	v_lshrrev_b32_e32 v8, 1, v5
	v_and_b32_e32 v9, 3, v5
	v_add_u32_e32 v22, 32, v5
	s_add_u32 s30, s18, s16
	v_and_b32_e32 v8, 7, v5
	v_and_b32_e32 v9, 0xfffff8, v22
	v_lshlrev_b32_e32 v10, 1, v22
	s_addc_u32 s31, s19, s17
	v_lshlrev_b32_e32 v2, 3, v4
	s_add_u32 s8, s28, s8
	v_and_b32_e32 v6, 0x78, v2
	v_lshrrev_b32_e32 v7, 1, v7
	v_bfe_u32 v2, v2, 5, 2
	v_lshrrev_b32_e32 v9, 1, v9
	s_addc_u32 s9, s29, s9
	v_or_b32_e32 v7, v7, v2
	v_lshlrev_b32_e32 v166, 1, v6
	v_or_b32_e32 v2, v9, v2
	s_add_u32 s42, s8, s16
	v_lshlrev_b32_e32 v8, 6, v8
	v_and_b32_e32 v6, 48, v166
	v_lshlrev_b32_e32 v2, 9, v2
	s_addc_u32 s43, s9, s17
	v_lshlrev_b32_e32 v7, 9, v7
	v_or3_b32 v178, v2, v8, v6
	v_lshl_or_b32 v2, v5, 10, v166
	v_or3_b32 v179, v7, v8, v6
	v_and_b32_e32 v42, 3, v4
	v_bfe_u32 v43, v4, 2, 2
	v_and_b32_e32 v44, 7, v5
	v_lshrrev_b32_e32 v45, 3, v5
	v_lshl_or_b32 v44, v44, 2, v43
	v_lshl_or_b32 v46, v45, 2, v42
	v_lshlrev_b32_e32 v46, 4, v46
	v_lshl_or_b32 v186, v44, 10, v46
	v_lshrrev_b32_e32 v47, 3, v44
	v_lshl_or_b32 v47, v47, 2, v45
	v_and_b32_e32 v46, 7, v44
	v_lshlrev_b32_e32 v47, 9, v47
	v_lshl_or_b32 v47, v46, 6, v47
	v_lshl_or_b32 v179, v42, 4, v47
	v_add_u32_e32 v178, 0x2000, v179
	v_mov_b32_e32 v42, v186
	v_mov_b32_e32 v43, 0
	v_lshl_add_u64 v[36:37], s[42:43], 0, v[42:43]
	global_load_dwordx4 v[6:9], v186, s[42:43]
	global_load_dwordx4 v[14:17], v2, s[30:31]
	v_add_co_u32_e32 v10, vcc, s33, v36
	v_lshl_add_u64 v[38:39], s[30:31], 0, v[2:3]
	s_nop 0
	v_addc_co_u32_e32 v11, vcc, 0, v37, vcc
	global_load_dwordx4 v[10:13], v[10:11], off
	v_add_co_u32_e32 v18, vcc, s33, v38
	v_add_u32_e32 v40, 0, v179
	s_nop 0
	v_addc_co_u32_e32 v19, vcc, 0, v39, vcc
	global_load_dwordx4 v[18:21], v[18:19], off
	s_waitcnt vmcnt(0)
	v_lshlrev_b32_e32 v5, 8, v5
	v_add_u32_e32 v41, 0, v178
	s_mov_b32 s8, 0x10000
	v_readfirstlane_b32 s18, v4
	s_waitcnt vmcnt(0)
	ds_write_b128 v40, v[6:9]
	v_and_b32_e32 v6, 0x70, v4
	v_bitop3_b32 v180, v166, v5, v6 bitop3:0xde
	v_add_u32_e32 v5, 0, v180
	ds_write_b128 v41, v[10:13]
	ds_write_b128 v5, v[14:17] offset:49152
	v_lshlrev_b32_e32 v5, 8, v22
	v_bitop3_b32 v181, v166, v5, v6 bitop3:0xde
	v_add_co_u32_e32 v6, vcc, s8, v36
	v_add_u32_e32 v5, 0, v181
	s_nop 0
	v_addc_co_u32_e32 v7, vcc, 0, v37, vcc
	ds_write_b128 v5, v[18:21] offset:49152
	global_load_dwordx4 v[20:23], v[6:7], off
	v_add_co_u32_e32 v6, vcc, 0x18000, v36
	s_nop 1
	v_addc_co_u32_e32 v7, vcc, 0, v37, vcc
	global_load_dwordx4 v[24:27], v[6:7], off
	v_add_co_u32_e32 v6, vcc, 0x10000, v38
	s_nop 1
	v_addc_co_u32_e32 v7, vcc, 0, v39, vcc
	global_load_dwordx4 v[28:31], v[6:7], off
	v_add_co_u32_e32 v6, vcc, 0x18000, v38
	s_nop 1
	v_addc_co_u32_e32 v7, vcc, 0, v39, vcc
	global_load_dwordx4 v[32:35], v[6:7], off
	s_waitcnt lgkmcnt(0)
	s_barrier
	s_and_b32 s8, s18, 0xffffff00
	s_cmpk_lg_i32 s8, 0x100
	s_cbranch_scc1 .LBB0_628
	s_waitcnt lgkmcnt(0)
	s_barrier

.LBB0_633:
	s_waitcnt lgkmcnt(0)
	s_barrier
	v_lshl_add_u32 v187, s53, 14, v173
	ds_read_b64_tr_b16 v[188:189], v187 offset:0
	ds_read_b64_tr_b16 v[190:191], v187 offset:0x800
	ds_read_b64_tr_b16 v[192:193], v187 offset:0x1000
	ds_read_b64_tr_b16 v[194:195], v187 offset:0x1800
	ds_read_b64_tr_b16 v[196:197], v187 offset:0x2000
	ds_read_b64_tr_b16 v[198:199], v187 offset:0x2800
	ds_read_b64_tr_b16 v[200:201], v187 offset:0x3000
	ds_read_b64_tr_b16 v[202:203], v187 offset:0x3800
	s_lshl_b32 s52, s49, 14
	v_add_u32_e32 v208, s52, v174
	ds_read_b128 v[68:71], v208 offset:0
	ds_read_b128 v[72:75], v208 offset:0x2000
	v_add_u32_e32 v209, s52, v175
	ds_read_b128 v[204:207], v209 offset:0
	ds_read_b128 v[216:219], v209 offset:0x2000
	v_add_u32_e32 v210, s52, v176
	ds_read_b128 v[220:223], v210 offset:0
	ds_read_b128 v[224:227], v210 offset:0x2000
	v_add_u32_e32 v211, s52, v177
	ds_read_b128 v[228:231], v211 offset:0
	ds_read_b128 v[232:235], v211 offset:0x2000
	s_waitcnt lgkmcnt(4)
	v_mfma_f32_32x32x16_bf16 v[84:99], v[68:71], v[128:131], 0
	v_mfma_f32_32x32x16_bf16 v[68:83], v[72:75], v[128:131], 0
	v_mfma_f32_32x32x16_bf16 v[84:99], v[204:207], v[124:127], v[84:99]
	v_mfma_f32_32x32x16_bf16 v[68:83], v[216:219], v[124:127], v[68:83]
	ds_read_b128 v[204:207], v208 offset:0x80
	ds_read_b128 v[216:219], v208 offset:0x2080
	ds_read_b128 v[236:239], v209 offset:0x80
	ds_read_b128 v[242:245], v209 offset:0x2080
	s_waitcnt lgkmcnt(4)
	v_mfma_f32_32x32x16_bf16 v[84:99], v[220:223], v[120:123], v[84:99]
	v_mfma_f32_32x32x16_bf16 v[68:83], v[224:227], v[120:123], v[68:83]
	v_mfma_f32_32x32x16_bf16 v[84:99], v[228:231], v[116:119], v[84:99]
	v_mfma_f32_32x32x16_bf16 v[68:83], v[232:235], v[116:119], v[68:83]
	ds_read_b128 v[220:223], v210 offset:0x80
	ds_read_b128 v[224:227], v210 offset:0x2080
	ds_read_b128 v[228:231], v211 offset:0x80
	ds_read_b128 v[232:235], v211 offset:0x2080
	s_waitcnt lgkmcnt(4)
	v_mfma_f32_32x32x16_bf16 v[84:99], v[204:207], v[112:115], v[84:99]
	v_mfma_f32_32x32x16_bf16 v[68:83], v[216:219], v[112:115], v[68:83]
	v_mfma_f32_32x32x16_bf16 v[84:99], v[236:239], v[108:111], v[84:99]
	v_mfma_f32_32x32x16_bf16 v[68:83], v[242:245], v[108:111], v[68:83]
	s_waitcnt lgkmcnt(0)
	v_mfma_f32_32x32x16_bf16 v[84:99], v[220:223], v[104:107], v[84:99]
	v_mfma_f32_32x32x16_bf16 v[68:83], v[224:227], v[104:107], v[68:83]
	v_mfma_f32_32x32x16_bf16 v[84:99], v[228:231], v[100:103], v[84:99]
	v_mfma_f32_32x32x16_bf16 v[68:83], v[232:235], v[100:103], v[68:83]
	ds_read_b64_tr_b16 v[204:205], v187 offset:0x200
	ds_read_b64_tr_b16 v[206:207], v187 offset:0xa00
	ds_read_b64_tr_b16 v[216:217], v187 offset:0x1200
	ds_read_b64_tr_b16 v[218:219], v187 offset:0x1a00
	ds_read_b64_tr_b16 v[220:221], v187 offset:0x2200
	ds_read_b64_tr_b16 v[222:223], v187 offset:0x2a00
	ds_read_b64_tr_b16 v[224:225], v187 offset:0x3200
	ds_read_b64_tr_b16 v[226:227], v187 offset:0x3a00
	s_waitcnt lgkmcnt(8)
	v_mfma_f32_32x32x16_bf16 v[4:19], v[148:151], v[188:191], v[4:19]
	s_lshl_b32 s19, s51, 14
	s_add_i32 s8, s19, 0
	v_add_u32_e32 v236, s8, v179
	s_waitcnt vmcnt(0)
	v_mfma_f32_32x32x16_bf16 v[4:19], v[152:155], v[192:195], v[4:19]
	ds_write_b128 v236, v[144:147]
	v_add_u32_e32 v236, s8, v178
	v_mfma_f32_32x32x16_bf16 v[4:19], v[156:159], v[196:199], v[4:19]
	ds_write_b128 v236, v[136:139]
	v_add_u32_e32 v236, s8, v180
	v_mfma_f32_32x32x16_bf16 v[4:19], v[160:163], v[200:203], v[4:19]
	ds_read_b64_tr_b16 v[188:189], v187 offset:0x400
	ds_read_b64_tr_b16 v[190:191], v187 offset:0xc00
	ds_read_b64_tr_b16 v[192:193], v187 offset:0x1400
	ds_read_b64_tr_b16 v[194:195], v187 offset:0x1c00
	ds_read_b64_tr_b16 v[196:197], v187 offset:0x2400
	ds_read_b64_tr_b16 v[198:199], v187 offset:0x2c00
	ds_read_b64_tr_b16 v[200:201], v187 offset:0x3400
	ds_read_b64_tr_b16 v[202:203], v187 offset:0x3c00
	s_waitcnt lgkmcnt(10)
	v_mfma_f32_32x32x16_bf16 v[52:67], v[148:151], v[204:207], v[52:67]
	ds_write_b128 v236, v[140:143] offset:49152
	v_add_u32_e32 v236, s8, v181
	v_mfma_f32_32x32x16_bf16 v[52:67], v[152:155], v[216:219], v[52:67]
	ds_write_b128 v236, v[132:135] offset:49152
	s_add_i32 s48, s48, 1
	v_mfma_f32_32x32x16_bf16 v[52:67], v[156:159], v[220:223], v[52:67]
	s_sub_i32 s8, s50, s47
	s_min_u32 s36, s50, s8
	s_lshl_b64 s[8:9], s[36:37], 10
	s_cmp_lt_u32 s50, s47
	s_cselect_b32 s16, s30, s20
	s_cselect_b32 s17, s31, s21
	v_mfma_f32_32x32x16_bf16 v[52:67], v[160:163], v[224:227], v[52:67]
	ds_read_b64_tr_b16 v[204:205], v187 offset:0x600
	ds_read_b64_tr_b16 v[206:207], v187 offset:0xe00
	ds_read_b64_tr_b16 v[216:217], v187 offset:0x1600
	ds_read_b64_tr_b16 v[218:219], v187 offset:0x1e00
	ds_read_b64_tr_b16 v[220:221], v187 offset:0x2600
	ds_read_b64_tr_b16 v[222:223], v187 offset:0x2e00
	ds_read_b64_tr_b16 v[224:225], v187 offset:0x3600
	ds_read_b64_tr_b16 v[226:227], v187 offset:0x3e00
	s_waitcnt lgkmcnt(10)
	v_mfma_f32_32x32x16_bf16 v[36:51], v[148:151], v[188:191], v[36:51]
	s_cselect_b32 s36, s42, s26
	s_cselect_b32 s54, s43, s27
	s_add_u32 s16, s16, s8
	s_addc_u32 s17, s17, s9
	s_add_u32 s8, s36, s8
	s_addc_u32 s9, s54, s9
	v_mfma_f32_32x32x16_bf16 v[36:51], v[152:155], v[192:195], v[36:51]
	global_load_dwordx4 v[144:147], v186, s[8:9]
	s_add_u32 s8, s8, 0x8000
	s_addc_u32 s9, s9, 0
	v_mfma_f32_32x32x16_bf16 v[36:51], v[156:159], v[196:199], v[36:51]
	global_load_dwordx4 v[136:139], v186, s[8:9]
	global_load_dwordx4 v[140:143], v2, s[16:17]
	v_mfma_f32_32x32x16_bf16 v[36:51], v[160:163], v[200:203], v[36:51]
	s_add_u32 s16, s16, 0x8000
	s_addc_u32 s17, s17, 0
	global_load_dwordx4 v[132:135], v2, s[16:17]
	s_waitcnt lgkmcnt(0)
	v_mfma_f32_32x32x16_bf16 v[20:35], v[148:151], v[204:207], v[20:35]
	v_mfma_f32_32x32x16_bf16 v[20:35], v[152:155], v[216:219], v[20:35]
	v_mfma_f32_32x32x16_bf16 v[20:35], v[156:159], v[220:223], v[20:35]
	v_mfma_f32_32x32x16_bf16 v[20:35], v[160:163], v[224:227], v[20:35]
